# code placement: S5 steady-state loop heads and the two adaLN-RMSNorm loop heads padded to 64-byte alignment
# baseline (speedup 1.0000x reference)
; DI unsigned pk2(float lo, float hi) { f32x2 v = {lo, hi}; bf16x2_t b = __builtin_convertvector(v, bf16x2_t); return __builtin_bit_cast(unsigned, b); }
; DI void normmod_phase(const float* xl, const float* xc, const float* g, const float* modl  , int cshift, int cscale, bf16_t* H, int nrows, int gw, int NGW, int lane,
;                       const float* part  , const float* pgate  , float* xc_out) {
;     auto ld = [&](const int row, f32x4 (&v)[4]) __attribute__((always_inline)) -> float {
;         const bool lat = row < ML;
;         const float* xr = lat ? xl + (size_t)row * D : xc + (size_t)(row - ML) * D;
;         float ss = 0.f;
; #pragma unroll
;         for (int j = 0; j < 4; ++j) { v[j] = *(const f32x4*)(xr + lane * 4 + 256 * j);
;             if (part && !lat) {
;                 const size_t po = (size_t)(row - ML) * D + lane * 4 + 256 * j;
;                 const f32x4 p0 = *(const f32x4*)(part + po), p1 = *(const f32x4*)(part + (size_t)MC * D + po), p2 = *(const f32x4*)(part + (size_t)2 * MC * D + po), p3 = *(const f32x4*)(part + (size_t)3 * MC * D + po);
;                 v[j] = v[j] + *(const f32x4*)(pgate + lane * 4 + 256 * j) * ((p0 + p1) + (p2 + p3));
;                 *(f32x4*)(xc_out + po) = v[j]; }
;             ss += (v[j][0] * v[j][0] + v[j][1] * v[j][1]) + (v[j][2] * v[j][2] + v[j][3] * v[j][3]); }
;         return ss; };
;     auto st = [&](const int row, const f32x4 (&v)[4], const float rs) __attribute__((always_inline)) {
;         const float* mp = modl + (size_t)((row < ML) ? (row >> 12) : 16) * 6144;
; #pragma unroll
;         for (int j = 0; j < 4; ++j) { const int c = lane * 4 + 256 * j;
;             const f32x4 gg = *(const f32x4*)(g + c), sh = *(const f32x4*)(mp + cshift * 1024 + c), scl = *(const f32x4*)(mp + cscale * 1024 + c);
;             const f32x4 y = (v[j] * rs) * gg * (scl + 1.f) + sh;
;             u32x2 o; o.x = pk2(y[0], y[1]); o.y = pk2(y[2], y[3]);
;             *(u32x2*)(H + (size_t)row * D + c) = o; } };
;     for (int row = gw * 4; row < (nrows < ML ? nrows : ML); row += NGW * 4) {
;         f32x4 vA[4], vB[4], vC[4], vD[4];
;         float sA = ld(row, vA), sB = ld(row + 1, vB), sC = ld(row + 2, vC), sD = ld(row + 3, vD);
.LBB0_314:
	s_lshl_b32 s8, s69, 12
	s_add_u32 s4, s4, s8
	s_addc_u32 s5, s5, 0
	s_add_u32 s8, s84, 0x312dc000
	v_readlane_b32 s56, v253, 23
	s_addc_u32 s9, s85, 0
	v_readlane_b32 s57, v253, 24
	s_and_b64 s[26:27], s[56:57], exec
	s_cselect_b32 s25, 0, s8
	s_cselect_b32 s20, 0, s9
	s_add_u32 s38, s25, 0x1000000
	s_addc_u32 s39, s20, 0
	s_add_u32 s40, s25, 0x2000000
	s_addc_u32 s41, s20, 0
	s_add_u32 s42, s25, 0x3000000
	v_lshlrev_b32_e32 v69, 2, v152
	v_lshlrev_b32_e32 v74, 4, v152
	v_mov_b32_e32 v75, v149
	s_addc_u32 s43, s20, 0
	v_lshl_add_u64 v[0:1], s[16:17], 0, v[74:75]
	s_mov_b64 s[26:27], 0x62000
	v_or_b32_e32 v68, 0x100, v69
	v_or_b32_e32 v70, 0x200, v69
	v_or_b32_e32 v72, 0x300, v69
	s_cmpk_gt_i32 s36, 0x3fff
	v_lshl_add_u64 v[64:65], v[0:1], 0, s[26:27]
	v_lshl_add_u64 v[66:67], s[4:5], 0, v[74:75]
	v_lshlrev_b32_e32 v71, 2, v68
	v_lshlrev_b32_e32 v73, 2, v70
	v_lshlrev_b32_e32 v80, 2, v72
	s_cbranch_scc1 .LBB0_353
	v_xor_b32_e32 v0, 1, v210
	v_cmp_lt_i32_e32 vcc, v0, v250
	s_lshl_b32 s5, s96, 5
	s_lshl_b32 s20, s37, 2
	v_cndmask_b32_e32 v0, v210, v0, vcc
	v_lshlrev_b32_e32 v81, 2, v0
	v_xor_b32_e32 v0, 2, v210
	v_cmp_lt_i32_e32 vcc, v0, v250
	s_lshl_b32 s4, s36, 2
	s_add_i32 s5, s5, s20
	v_cndmask_b32_e32 v0, v210, v0, vcc
	v_cmp_lt_i32_e32 vcc, v251, v250
	v_lshlrev_b32_e32 v82, 2, v0
	s_add_i32 s20, s5, 0xffff0001
	v_cndmask_b32_e32 v0, v210, v251, vcc
	v_lshlrev_b32_e32 v83, 2, v0
	v_xor_b32_e32 v0, 8, v210
	s_ashr_i32 s5, s4, 31
	s_lshl_b32 s26, s33, 5
	v_cmp_lt_i32_e32 vcc, v0, v250
	s_lshl_b64 s[30:31], s[4:5], 12
	s_add_u32 s44, s10, s30
	v_cndmask_b32_e32 v0, v210, v0, vcc
	v_lshlrev_b32_e32 v84, 2, v0
	v_xor_b32_e32 v0, 16, v210
	s_addc_u32 s45, s11, s31
	s_ashr_i32 s27, s26, 31
	v_cmp_lt_i32_e32 vcc, v0, v250
	s_lshl_b64 s[46:47], s[26:27], 12
	s_lshl_b64 s[4:5], s[4:5], 11
	v_readlane_b32 s12, v254, 26
	v_cndmask_b32_e32 v0, v210, v0, vcc
	s_add_u32 s25, s12, s78
	v_readlane_b32 s12, v254, 27
	v_lshlrev_b32_e32 v85, 2, v0
	v_xor_b32_e32 v0, 32, v210
	s_addc_u32 s30, s12, s79
	v_cmp_lt_i32_e32 vcc, v0, v250
	s_add_u32 s4, s25, s4
	v_lshlrev_b32_e32 v148, 3, v152
	v_cndmask_b32_e32 v0, v210, v0, vcc
	s_addc_u32 s5, s30, s5
	v_lshlrev_b32_e32 v86, 2, v0
	v_lshl_add_u64 v[76:77], s[4:5], 0, v[148:149]
	s_lshl_b64 s[48:49], s[26:27], 11
	global_load_dwordx4 v[156:159], v[66:67], off
	global_load_dwordx4 v[160:163], v[66:67], off offset:1024
	global_load_dwordx4 v[164:167], v[66:67], off offset:2048
	global_load_dwordx4 v[168:171], v[66:67], off offset:3072
	s_add_u32 s4, s44, 0x1000
	s_addc_u32 s5, s45, 0
	s_add_u32 s34, s44, 0x2000
	s_addc_u32 s35, s45, 0
	s_add_u32 s54, s44, 0x3000
	s_addc_u32 s55, s45, 0
	global_load_dwordx4 v[0:3], v74, s[44:45] nt
	global_load_dwordx4 v[4:7], v74, s[44:45] offset:1024 nt
	global_load_dwordx4 v[8:11], v74, s[44:45] offset:2048 nt
	global_load_dwordx4 v[12:15], v74, s[44:45] offset:3072 nt
	global_load_dwordx4 v[16:19], v74, s[4:5] nt
	global_load_dwordx4 v[20:23], v74, s[4:5] offset:1024 nt
	global_load_dwordx4 v[24:27], v74, s[4:5] offset:2048 nt
	global_load_dwordx4 v[28:31], v74, s[4:5] offset:3072 nt
	global_load_dwordx4 v[32:35], v74, s[34:35] nt
	global_load_dwordx4 v[36:39], v74, s[34:35] offset:1024 nt
	global_load_dwordx4 v[40:43], v74, s[34:35] offset:2048 nt
	global_load_dwordx4 v[44:47], v74, s[34:35] offset:3072 nt
	global_load_dwordx4 v[48:51], v74, s[54:55] nt
	global_load_dwordx4 v[52:55], v74, s[54:55] offset:1024 nt
	global_load_dwordx4 v[56:59], v74, s[54:55] offset:2048 nt
	global_load_dwordx4 v[60:63], v74, s[54:55] offset:3072 nt
	s_branch .LBB0_317
	s_nop 0
	s_nop 0
	s_nop 0
	s_nop 0
	s_nop 0
	s_nop 0
	s_nop 0
	s_nop 0
	s_nop 0
	s_nop 0

; #define LAS __attribute__((address_space(3)))
; #define MFMA16(a, b, c) __builtin_amdgcn_mfma_f32_16x16x32_bf16((a), (b), (c), 0, 0, 0)
; #define S5_CB() asm volatile("" ::: "memory")
; DI void s5_phase(const KArgs& a, int zz, int o, const bf16_t* H, bf16_t* YF, bf16_t* YB, LAS unsigned char* lds, int G, int bid, int wave, int lane) {
;     ...
;         auto chunk_row = [&](int ci) -> size_t { const bool seg = ci < 16; const int k = seg ? ci : ci - 16, nch = seg ? 16 : 256, cidx = DIRC ? nch - 1 - k : k;
;             return seg ? (size_t)ML + b * TC + cidx * 16 : (size_t)b * T + cidx * 16; };
;     ...
;         auto loadu = [&](const int ci) __attribute__((always_inline)) -> u32x4 {
;             const int cc = ci < 272 ? ci : 271;
;             u32x4 r = *(const u32x4*)(Hg + (chunk_row(cc) + fr) * D);
;             const bool keep = fq < 2;
;             r.x = keep ? r.x : 0u; r.y = keep ? r.y : 0u; r.z = keep ? r.z : 0u; r.w = keep ? r.w : 0u;
;             return r; };
;         auto stageA = [&](const u32x4 uu) __attribute__((always_inline)) {
;             const bf16x8 Au = __builtin_bit_cast(bf16x8, uu);
; #pragma unroll
;             for (int nt = 0; nt < 8; ++nt) { const f32x4 acc = MFMA16(Bb[nt], Au, ((f32x4){0.f, 0.f, 0.f, 0.f}));
;                 *(LAS f32x4*)(BU + fr * 132 + 16 * nt + fq * 4) = acc; } };
;         u32x4 u1 = loadu(1), u2 = loadu(2);
;         stageA(loadu(0));
;         S5_CB();
;         size_t rowprev = 0;
;         auto iter = [&](const int ci, const bool do_c) __attribute__((always_inline)) {
;             const size_t row0 = chunk_row(ci);
;             const u32x4 u3 = loadu(ci + 3);
.Ls5f_bwd_entry:
	s_add_u32 s98, s58, 0xfb0
	s_addc_u32 s99, s59, 0
	s_mov_b32 s100, 0x20000
	s_mov_b32 s101, 0
	s_lshl_b64 s[98:99], s[98:99], 11
	v_lshlrev_b64 v[56:57], 11, v[104:105]
	v_lshl_add_u64 v[246:247], v[126:127], 0, v[56:57]
	v_lshl_add_u64 v[248:249], v[128:129], 0, v[56:57]
	v_lshl_add_u64 v[248:249], v[248:249], 0, s[100:101]
	s_mov_b32 s100, 17
	s_nop 0
	s_nop 0
	s_nop 0
	s_nop 0
	s_nop 0
	s_nop 0
	s_nop 0
	s_nop 0
	s_nop 0
	s_nop 0

; #define LAS __attribute__((address_space(3)))
; #define MFMA16(a, b, c) __builtin_amdgcn_mfma_f32_16x16x32_bf16((a), (b), (c), 0, 0, 0)
; #define S5_CB() asm volatile("" ::: "memory")
; DI void s5_phase(const KArgs& a, int zz, int o, const bf16_t* H, bf16_t* YF, bf16_t* YB, LAS unsigned char* lds, int G, int bid, int wave, int lane) {
;     ...
;         auto chunk_row = [&](int ci) -> size_t { const bool seg = ci < 16; const int k = seg ? ci : ci - 16, nch = seg ? 16 : 256, cidx = DIRC ? nch - 1 - k : k;
;             return seg ? (size_t)ML + b * TC + cidx * 16 : (size_t)b * T + cidx * 16; };
;     ...
;         auto loadu = [&](const int ci) __attribute__((always_inline)) -> u32x4 {
;             const int cc = ci < 272 ? ci : 271;
;             u32x4 r = *(const u32x4*)(Hg + (chunk_row(cc) + fr) * D);
;             const bool keep = fq < 2;
;             r.x = keep ? r.x : 0u; r.y = keep ? r.y : 0u; r.z = keep ? r.z : 0u; r.w = keep ? r.w : 0u;
;             return r; };
;         auto stageA = [&](const u32x4 uu) __attribute__((always_inline)) {
;             const bf16x8 Au = __builtin_bit_cast(bf16x8, uu);
; #pragma unroll
;             for (int nt = 0; nt < 8; ++nt) { const f32x4 acc = MFMA16(Bb[nt], Au, ((f32x4){0.f, 0.f, 0.f, 0.f}));
;                 *(LAS f32x4*)(BU + fr * 132 + 16 * nt + fq * 4) = acc; } };
;         u32x4 u1 = loadu(1), u2 = loadu(2);
;         stageA(loadu(0));
;         S5_CB();
;         size_t rowprev = 0;
;         auto iter = [&](const int ci, const bool do_c) __attribute__((always_inline)) {
;             const size_t row0 = chunk_row(ci);
;             const u32x4 u3 = loadu(ci + 3);
.Ls5f_fwd_entry:
	s_add_u32 s98, s56, 64
	s_addc_u32 s99, s57, 0
	s_mov_b32 s100, 0xfffe0000
	s_mov_b32 s101, -1
	s_lshl_b64 s[98:99], s[98:99], 11
	v_lshlrev_b64 v[56:57], 11, v[104:105]
	v_lshl_add_u64 v[246:247], v[126:127], 0, v[56:57]
	v_lshl_add_u64 v[248:249], v[128:129], 0, v[56:57]
	v_lshl_add_u64 v[248:249], v[248:249], 0, s[100:101]
	s_mov_b32 s100, 17
	s_nop 0
	s_nop 0
	s_nop 0
	s_nop 0
	s_nop 0
	s_nop 0
	s_nop 0
	s_nop 0
	s_nop 0
	s_nop 0
	s_nop 0
	s_nop 0

; DI unsigned pk2(float lo, float hi) { f32x2 v = {lo, hi}; bf16x2_t b = __builtin_convertvector(v, bf16x2_t); return __builtin_bit_cast(unsigned, b); }
; DI void normmod_phase(const float* xl, const float* xc, const float* g, const float* modl  , int cshift, int cscale, bf16_t* H, int nrows, int gw, int NGW, int lane,
;                       const float* part  , const float* pgate  , float* xc_out) {
;     auto ld = [&](const int row, f32x4 (&v)[4]) __attribute__((always_inline)) -> float {
;         const bool lat = row < ML;
;         const float* xr = lat ? xl + (size_t)row * D : xc + (size_t)(row - ML) * D;
;         float ss = 0.f;
; #pragma unroll
;         for (int j = 0; j < 4; ++j) { v[j] = *(const f32x4*)(xr + lane * 4 + 256 * j);
;             if (part && !lat) {
;                 const size_t po = (size_t)(row - ML) * D + lane * 4 + 256 * j;
;                 const f32x4 p0 = *(const f32x4*)(part + po), p1 = *(const f32x4*)(part + (size_t)MC * D + po), p2 = *(const f32x4*)(part + (size_t)2 * MC * D + po), p3 = *(const f32x4*)(part + (size_t)3 * MC * D + po);
;                 v[j] = v[j] + *(const f32x4*)(pgate + lane * 4 + 256 * j) * ((p0 + p1) + (p2 + p3));
;                 *(f32x4*)(xc_out + po) = v[j]; }
;             ss += (v[j][0] * v[j][0] + v[j][1] * v[j][1]) + (v[j][2] * v[j][2] + v[j][3] * v[j][3]); }
;         return ss; };
;     auto st = [&](const int row, const f32x4 (&v)[4], const float rs) __attribute__((always_inline)) {
;         const float* mp = modl + (size_t)((row < ML) ? (row >> 12) : 16) * 6144;
; #pragma unroll
;         for (int j = 0; j < 4; ++j) { const int c = lane * 4 + 256 * j;
;             const f32x4 gg = *(const f32x4*)(g + c), sh = *(const f32x4*)(mp + cshift * 1024 + c), scl = *(const f32x4*)(mp + cscale * 1024 + c);
;             const f32x4 y = (v[j] * rs) * gg * (scl + 1.f) + sh;
;             u32x2 o; o.x = pk2(y[0], y[1]); o.y = pk2(y[2], y[3]);
;             *(u32x2*)(H + (size_t)row * D + c) = o; } };
;     for (int row = gw * 4; row < (nrows < ML ? nrows : ML); row += NGW * 4) {
;         f32x4 vA[4], vB[4], vC[4], vD[4];
;         float sA = ld(row, vA), sB = ld(row + 1, vB), sC = ld(row + 2, vC), sD = ld(row + 3, vD);
.LBB0_553:
	s_andn2_b64 vcc, exec, s[4:5]
	s_cbranch_vccnz .LBB0_621
	s_lshl_b64 s[4:5], s[78:79], 3
	v_readlane_b32 s6, v253, 5
	v_readlane_b32 s7, v253, 6
	s_add_u32 s4, s6, s4
	s_addc_u32 s5, s7, s5
	s_load_dwordx2 s[4:5], s[4:5], 0x30
	s_lshl_b32 s6, s69, 12
	v_readlane_b32 s54, v253, 28
	v_readlane_b32 s55, v253, 29
	v_lshlrev_b32_e32 v69, 2, v152
	s_waitcnt lgkmcnt(0)
	s_add_u32 s4, s4, s6
	v_readlane_b32 s6, v253, 23
	s_addc_u32 s5, s5, 0
	v_readlane_b32 s7, v253, 24
	s_and_b64 s[6:7], s[6:7], exec
	s_cselect_b32 s23, 0, 0x15400000
	s_add_u32 s6, s84, 0x312dc000
	s_addc_u32 s7, s85, 0
	s_and_b64 s[8:9], s[54:55], exec
	s_cselect_b32 s24, 0, s6
	s_cselect_b32 s20, 0, s7
	s_add_u32 s8, s24, 0x1000000
	s_addc_u32 s9, s20, 0
	s_add_u32 s38, s24, 0x2000000
	s_addc_u32 s39, s20, 0
	s_add_u32 s40, s24, 0x3000000
	s_addc_u32 s41, s20, 0
	v_lshlrev_b32_e32 v76, 4, v152
	v_mov_b32_e32 v77, v149
	v_or_b32_e32 v68, 0x100, v69
	v_or_b32_e32 v70, 0x200, v69
	v_or_b32_e32 v72, 0x300, v69
	s_mov_b32 s56, s36
	s_cmpk_gt_i32 s36, 0x3fff
	v_lshl_add_u64 v[64:65], s[16:17], 0, v[76:77]
	v_lshl_add_u64 v[66:67], s[4:5], 0, v[76:77]
	v_lshlrev_b32_e32 v74, 3, v152
	v_lshlrev_b32_e32 v71, 2, v68
	v_lshlrev_b32_e32 v73, 2, v70
	v_lshlrev_b32_e32 v82, 2, v72
	s_movk_i32 s13, 0xf000
	s_mov_b32 s34, 0x3a800000
	s_mov_b32 s36, 0x358637bd
	s_cbranch_scc1 .LBB0_593
	s_waitcnt vmcnt(5)
	v_xor_b32_e32 v0, 1, v210
	v_cmp_lt_i32_e32 vcc, v0, v250
	s_lshl_b32 s5, s96, 5
	s_lshl_b32 s20, s37, 2
	v_cndmask_b32_e32 v0, v210, v0, vcc
	v_lshlrev_b32_e32 v83, 2, v0
	v_xor_b32_e32 v0, 2, v210
	s_lshl_b32 s4, s56, 2
	v_cmp_lt_i32_e32 vcc, v0, v250
	s_add_i32 s5, s5, s20
	s_add_i32 s20, s5, 0xffff0001
	v_cndmask_b32_e32 v0, v210, v0, vcc
	v_cmp_lt_i32_e32 vcc, v251, v250
	s_ashr_i32 s5, s4, 31
	s_lshl_b32 s26, s33, 5
	v_lshlrev_b32_e32 v84, 2, v0
	v_cndmask_b32_e32 v0, v210, v251, vcc
	s_lshl_b64 s[24:25], s[4:5], 12
	v_lshlrev_b32_e32 v85, 2, v0
	v_xor_b32_e32 v0, 8, v210
	s_add_u32 s42, s10, s24
	v_cmp_lt_i32_e32 vcc, v0, v250
	s_addc_u32 s43, s11, s25
	s_ashr_i32 s27, s26, 31
	v_cndmask_b32_e32 v0, v210, v0, vcc
	s_lshl_b64 s[44:45], s[26:27], 12
	s_lshl_b64 s[4:5], s[4:5], 11
	v_lshlrev_b32_e32 v86, 2, v0
	v_xor_b32_e32 v0, 16, v210
	s_add_u32 s4, s23, s4
	v_cmp_lt_i32_e32 vcc, v0, v250
	s_addc_u32 s5, 0, s5
	v_readlane_b32 s12, v254, 26
	v_cndmask_b32_e32 v0, v210, v0, vcc
	s_add_u32 s24, s12, s78
	v_readlane_b32 s12, v254, 27
	v_lshlrev_b32_e32 v87, 2, v0
	v_xor_b32_e32 v0, 32, v210
	s_addc_u32 s25, s12, s79
	v_cmp_lt_i32_e32 vcc, v0, v250
	s_add_u32 s4, s24, s4
	v_mov_b32_e32 v75, v149
	v_cndmask_b32_e32 v0, v210, v0, vcc
	s_addc_u32 s5, s25, s5
	v_lshlrev_b32_e32 v88, 2, v0
	v_lshl_add_u64 v[78:79], s[4:5], 0, v[74:75]
	s_lshl_b64 s[46:47], s[26:27], 11
	global_load_dwordx4 v[156:159], v[66:67], off
	global_load_dwordx4 v[160:163], v[66:67], off offset:1024
	global_load_dwordx4 v[164:167], v[66:67], off offset:2048
	global_load_dwordx4 v[168:171], v[66:67], off offset:3072
	s_add_u32 s4, s42, 0x1000
	s_addc_u32 s5, s43, 0
	s_add_u32 s24, s42, 0x2000
	s_addc_u32 s25, s43, 0
	s_add_u32 s48, s42, 0x3000
	s_addc_u32 s49, s43, 0
	global_load_dwordx4 v[0:3], v76, s[42:43] nt
	global_load_dwordx4 v[4:7], v76, s[42:43] offset:1024 nt
	global_load_dwordx4 v[8:11], v76, s[42:43] offset:2048 nt
	global_load_dwordx4 v[12:15], v76, s[42:43] offset:3072 nt
	global_load_dwordx4 v[16:19], v76, s[4:5] nt
	global_load_dwordx4 v[20:23], v76, s[4:5] offset:1024 nt
	global_load_dwordx4 v[24:27], v76, s[4:5] offset:2048 nt
	global_load_dwordx4 v[28:31], v76, s[4:5] offset:3072 nt
	global_load_dwordx4 v[32:35], v76, s[24:25] nt
	global_load_dwordx4 v[36:39], v76, s[24:25] offset:1024 nt
	global_load_dwordx4 v[40:43], v76, s[24:25] offset:2048 nt
	global_load_dwordx4 v[44:47], v76, s[24:25] offset:3072 nt
	global_load_dwordx4 v[48:51], v76, s[48:49] nt
	global_load_dwordx4 v[52:55], v76, s[48:49] offset:1024 nt
	global_load_dwordx4 v[56:59], v76, s[48:49] offset:2048 nt
	global_load_dwordx4 v[60:63], v76, s[48:49] offset:3072 nt
	s_branch .LBB0_557
	s_nop 0
	s_nop 0
